# v136 + nt on phase-12 mLSTM dwordx4 input loads (read-once q/k/v chunk streams)
# baseline (speedup 1.0000x reference)
; DI void mlstm_item(const Ctx& c, int item, char* smem) {
;     ...
;   const bf16_t* raw = (const bf16_t*)(p.ws + OFF_MLRAW);
;   bf16_t* H = (bf16_t*)(p.ws + OFF_HFB) + (size_t)dir * NTOK * 1024;
;   const float ib = p.ml_i_b[dir * 8 + head], fb = p.ml_f_b[dir * 8 + head];
;   const int cvi = tid & 15, tg = tid >> 4, ch = head * 128 + cvi * 8;
;   float mprev = 0.f;
;   u32x4 px[6]; bf16_t pgi = 0, pgf = 0;
;     ...
;   ML_PREFETCH(0);
.LBB0_1275:
	s_or_b64 exec, exec, s[0:1]
	s_ashr_i32 s0, s90, 8
	s_and_b32 s62, s33, 7
	s_lshl_b32 s76, s0, 3
	s_or_b32 s58, s76, s62
	s_ashr_i32 s59, s58, 31
	v_readlane_b32 s68, v253, 48
	s_lshl_b64 s[58:59], s[58:59], 2
	v_readlane_b32 s70, v253, 50
	v_readlane_b32 s71, v253, 51
	s_add_u32 s60, s70, s58
	v_readlane_b32 s72, v253, 52
	s_addc_u32 s61, s71, s59
	v_readlane_b32 s73, v253, 53
	s_add_u32 s58, s72, s58
	s_addc_u32 s59, s73, s59
	global_load_dword v217, v0, s[60:61]
	global_load_dword v218, v0, s[58:59]
	s_lshl_b32 s33, s62, 7
	v_or_b32_e32 v1, s33, v117
	s_cmpk_lt_u32 s90, 0x100
	s_cselect_b64 s[58:59], -1, 0
	v_lshlrev_b32_e32 v2, 1, v1
	v_mov_b32_e32 v3, v0
	v_readlane_b32 s69, v253, 49
	s_cmpk_gt_u32 s90, 0xff
	s_waitcnt vmcnt(18)
	v_cndmask_b32_e64 v34, v187, v186, s[58:59]
	v_lshl_add_u64 v[128:129], s[64:65], 0, v[2:3]
	v_mov_b32_e32 v2, v0
	s_cselect_b64 s[68:69], -1, 0
	v_add_u32_e32 v16, -1, v34
	s_lshl_b32 s1, s90, 7
	v_mov_b32_e32 v1, v0
	v_mov_b64_e32 v[14:15], v[2:3]
	s_and_b32 s70, s1, 0x7800
	v_cmp_gt_u32_e32 vcc, s85, v16
	v_mov_b64_e32 v[12:13], v[0:1]
	v_readlane_b32 s74, v253, 54
	v_readlane_b32 s75, v253, 55
	s_and_saveexec_b64 s[60:61], vcc
	s_cbranch_execz .LBB0_1277
	v_or_b32_e32 v12, s70, v16
	v_mul_lo_u32 v12, v12, s86
	v_mov_b32_e32 v13, v0
	v_lshl_add_u64 v[12:13], v[12:13], 1, v[128:129]
	global_load_dwordx4 v[12:15], v[12:13], off nt
.LBB0_1277:
	s_or_b64 exec, exec, s[60:61]
	v_or_b32_e32 v16, s70, v34
	v_mul_lo_u32 v32, v16, s86
	v_mov_b64_e32 v[18:19], v[2:3]
	v_cmp_gt_u32_e64 s[60:61], s85, v34
	v_mov_b64_e32 v[16:17], v[0:1]
	s_and_saveexec_b64 s[78:79], s[60:61]
	s_cbranch_execz .LBB0_1279
	v_mov_b32_e32 v33, v0
	v_lshl_add_u64 v[2:3], v[32:33], 1, v[128:129]
	global_load_dwordx4 v[16:19], v[2:3], off nt
.LBB0_1279:
	s_or_b64 exec, exec, s[78:79]
	v_mov_b32_e32 v2, v0
	v_mov_b32_e32 v3, v0
	v_mov_b32_e32 v1, v0
	v_mov_b64_e32 v[22:23], v[2:3]
	v_mov_b64_e32 v[20:21], v[0:1]
	s_and_saveexec_b64 s[78:79], s[60:61]
	s_cbranch_execz .LBB0_1281
	v_mov_b32_e32 v33, v0
	v_lshl_add_u64 v[20:21], v[32:33], 1, v[128:129]
	v_add_co_u32_e32 v20, vcc, 0x1000, v20
	s_nop 1
	v_addc_co_u32_e32 v21, vcc, 0, v21, vcc
	global_load_dwordx4 v[20:23], v[20:21], off offset:64 nt
.LBB0_1281:
	s_or_b64 exec, exec, s[78:79]
	v_mov_b64_e32 v[26:27], v[2:3]
	v_mov_b64_e32 v[24:25], v[0:1]
	s_and_saveexec_b64 s[78:79], s[60:61]
	s_cbranch_execz .LBB0_1283
	v_mov_b32_e32 v33, v0
	v_lshl_add_u64 v[2:3], v[32:33], 1, v[128:129]
	v_add_co_u32_e32 v2, vcc, 0x2000, v2
	s_nop 1
	v_addc_co_u32_e32 v3, vcc, 0, v3, vcc
	global_load_dwordx4 v[24:27], v[2:3], off offset:128 nt
.LBB0_1283:
	s_or_b64 exec, exec, s[78:79]
	v_mov_b32_e32 v2, v0
	v_mov_b32_e32 v3, v0
	v_mov_b32_e32 v1, v0
	v_mov_b64_e32 v[30:31], v[2:3]
	v_mov_b64_e32 v[28:29], v[0:1]
	s_and_saveexec_b64 s[78:79], s[60:61]
	s_cbranch_execz .LBB0_1285
	v_mov_b32_e32 v33, v0
	v_lshl_add_u64 v[28:29], v[32:33], 1, v[128:129]
	v_add_co_u32_e32 v28, vcc, 0x3000, v28
	s_nop 1
	v_addc_co_u32_e32 v29, vcc, 0, v29, vcc
	global_load_dwordx4 v[28:31], v[28:29], off offset:192 nt
.LBB0_1285:
	s_or_b64 exec, exec, s[78:79]
	v_add_u32_e32 v36, 4, v34
	v_mov_b64_e32 v[34:35], v[2:3]
	v_cmp_gt_u32_e32 vcc, s85, v36
	v_mov_b64_e32 v[32:33], v[0:1]
	s_and_saveexec_b64 s[60:61], vcc
	s_cbranch_execz .LBB0_1287
	v_or_b32_e32 v1, s70, v36
	v_mul_lo_u32 v2, v1, s86
	v_mov_b32_e32 v3, v0
	v_lshl_add_u64 v[2:3], v[2:3], 1, v[128:129]
	global_load_dwordx4 v[32:35], v[2:3], off nt

; DI void mlstm_item(const Ctx& c, int item, char* smem) {
;     ...
;     if (c + 1 < SEQ / 64) ML_PREFETCH(c + 1);
.LBB0_1310:
	v_mov_b32_e32 v2, v0
	v_mov_b32_e32 v3, v0
	v_add_u32_e32 v16, -1, v32
	v_mov_b32_e32 v1, v0
	v_mov_b64_e32 v[14:15], v[2:3]
	v_cmp_gt_u32_e32 vcc, s85, v16
	v_mov_b64_e32 v[12:13], v[0:1]
	s_and_saveexec_b64 s[0:1], vcc
	s_cbranch_execz .LBB0_1312
	v_or_b32_e32 v12, s70, v16
	v_mul_lo_u32 v12, v12, s86
	v_mov_b32_e32 v13, v0
	v_lshl_add_u64 v[12:13], v[12:13], 1, v[128:129]
	global_load_dwordx4 v[12:15], v[12:13], off nt
.LBB0_1312:
	s_or_b64 exec, exec, s[0:1]
	v_mov_b64_e32 v[18:19], v[2:3]
	v_cmp_gt_u32_e32 vcc, s85, v32
	v_mov_b64_e32 v[16:17], v[0:1]
	s_and_saveexec_b64 s[0:1], vcc
	s_cbranch_execz .LBB0_1314
	v_or_b32_e32 v1, s70, v32
	v_mul_lo_u32 v2, v1, s86
	v_mov_b32_e32 v3, v0
	v_lshl_add_u64 v[2:3], v[2:3], 1, v[128:129]
	global_load_dwordx4 v[16:19], v[2:3], off nt
.LBB0_1314:
	s_or_b64 exec, exec, s[0:1]
	v_mov_b32_e32 v2, v0
	v_mov_b32_e32 v3, v0
	v_add_u32_e32 v24, 1, v32
	v_mov_b32_e32 v1, v0
	v_mov_b64_e32 v[22:23], v[2:3]
	v_cmp_gt_u32_e32 vcc, s85, v24
	v_mov_b64_e32 v[20:21], v[0:1]
	s_and_saveexec_b64 s[0:1], vcc
	s_cbranch_execz .LBB0_1316
	v_or_b32_e32 v20, s70, v24
	v_mul_lo_u32 v20, v20, s86
	v_mov_b32_e32 v21, v0
	v_lshl_add_u64 v[20:21], v[20:21], 1, v[128:129]
	global_load_dwordx4 v[20:23], v[20:21], off nt
.LBB0_1316:
	s_or_b64 exec, exec, s[0:1]
	v_add_u32_e32 v28, 2, v32
	v_mov_b64_e32 v[26:27], v[2:3]
	v_cmp_gt_u32_e32 vcc, s85, v28
	v_mov_b64_e32 v[24:25], v[0:1]
	s_and_saveexec_b64 s[0:1], vcc
	s_cbranch_execz .LBB0_1318
	v_or_b32_e32 v1, s70, v28
	v_mul_lo_u32 v2, v1, s86
	v_mov_b32_e32 v3, v0
	v_lshl_add_u64 v[2:3], v[2:3], 1, v[128:129]
	global_load_dwordx4 v[24:27], v[2:3], off nt
.LBB0_1318:
	s_or_b64 exec, exec, s[0:1]
	v_mov_b32_e32 v2, v0
	v_mov_b32_e32 v3, v0
	v_add_u32_e32 v33, 3, v32
	v_mov_b32_e32 v1, v0
	v_mov_b64_e32 v[30:31], v[2:3]
	v_cmp_gt_u32_e32 vcc, s85, v33
	v_mov_b64_e32 v[28:29], v[0:1]
	s_and_saveexec_b64 s[0:1], vcc
	s_cbranch_execz .LBB0_1320
	v_or_b32_e32 v28, s70, v33
	v_mul_lo_u32 v28, v28, s86
	v_mov_b32_e32 v29, v0
	v_lshl_add_u64 v[28:29], v[28:29], 1, v[128:129]
	global_load_dwordx4 v[28:31], v[28:29], off nt
.LBB0_1320:
	s_or_b64 exec, exec, s[0:1]
	v_add_u32_e32 v76, 4, v32
	v_mov_b64_e32 v[34:35], v[2:3]
	v_cmp_gt_u32_e32 vcc, s85, v76
	v_mov_b64_e32 v[32:33], v[0:1]
	s_and_saveexec_b64 s[0:1], vcc
	s_cbranch_execz .LBB0_1322
	v_or_b32_e32 v1, s70, v76
	v_mul_lo_u32 v2, v1, s86
	v_mov_b32_e32 v3, v0
	v_lshl_add_u64 v[2:3], v[2:3], 1, v[128:129]
	global_load_dwordx4 v[32:35], v[2:3], off nt

; DI u32x4 pack8(const float* f) { u32x4 w; w.x = pack2(f[0], f[1]); w.y = pack2(f[2], f[3]); w.z = pack2(f[4], f[5]); w.w = pack2(f[6], f[7]); return w; }
; #define S5_PREFETCH(c0_) do { const int st_ = (c0_) + fr, t_ = dir ? (SEQ - 1 - st_) : st_; \
;     pu = (fq < 2) ? ld8(U + ((size_t)b * SEQ + t_) * 512 + g * 16 + fq * 8) : (u32x4){0u, 0u, 0u, 0u}; } while (0)
; DI void s5_item(const Ctx& c, int item, char* smem) {
;     ...
;   bf16x8 cf[4];
; #pragma unroll
;   for (int ks = 0; ks < 4; ++ks) {
;     float cv[8];
; #pragma unroll
;     for (int jj = 0; jj < 8; ++jj) { const int k = ks * 32 + fq * 8 + jj; const size_t base = ((size_t)(dir * 32 + g) * 16 + fr) * 64; cv[jj] = k < 64 ? p.s5_C_re[base + k] : -p.s5_C_im[base + k - 64]; }
;     cf[ks] = __builtin_bit_cast(bf16x8, pack8(cv));
;   }
;   float xr = 0.f, xi = 0.f;
;   u32x4 pu;
;     ...
;   S5_PREFETCH(0);
.LBB0_1476:
	s_or_b64 exec, exec, s[6:7]
	v_lshlrev_b64 v[2:3], 12, v[2:3]
	v_lshl_or_b32 v2, v62, 2, v2
	v_lshl_add_u64 v[14:15], v[64:65], 0, v[2:3]
	v_lshl_add_u64 v[2:3], v[66:67], 0, v[2:3]
	global_load_dwordx4 v[44:47], v[14:15], off offset:16 nt
	global_load_dwordx4 v[10:13], v[14:15], off nt
	global_load_dwordx4 v[40:43], v[14:15], off offset:144 nt
	s_nop 0
	global_load_dwordx4 v[14:17], v[14:15], off offset:128 nt
	s_nop 0
	global_load_dwordx4 v[24:27], v[2:3], off offset:16 nt
	global_load_dwordx4 v[36:39], v[2:3], off nt
	global_load_dwordx4 v[28:31], v[2:3], off offset:144 nt
	global_load_dwordx4 v[32:35], v[2:3], off offset:128 nt
	s_bfe_u32 s16, s20, 0x40003
	s_cmpk_lt_u32 s0, 0x80
	v_lshlrev_b32_e32 v116, 4, v18
	s_cselect_b64 s[6:7], -1, 0
	v_ashrrev_i32_e32 v117, 31, v116
	s_and_saveexec_b64 s[8:9], s[2:3]
	s_xor_b64 s[8:9], exec, s[8:9]
	s_cbranch_execz .LBB0_1478
	v_cndmask_b32_e64 v0, v134, v133, s[6:7]
	v_lshlrev_b32_e32 v0, 1, v0
	v_lshl_or_b32 v0, s16, 21, v0
	v_lshl_add_u64 v[2:3], s[12:13], 0, v[0:1]
	v_lshl_add_u64 v[2:3], v[116:117], 1, v[2:3]
	v_lshlrev_b32_e32 v0, 1, v60
	v_lshl_add_u64 v[2:3], v[2:3], 0, v[0:1]
	global_load_dwordx4 v[18:21], v[2:3], off nt

; #define S5_PREFETCH(c0_) do { const int st_ = (c0_) + fr, t_ = dir ? (SEQ - 1 - st_) : st_; \
;     pu = (fq < 2) ? ld8(U + ((size_t)b * SEQ + t_) * 512 + g * 16 + fq * 8) : (u32x4){0u, 0u, 0u, 0u}; } while (0)
; DI void s5_item(const Ctx& c, int item, char* smem) {
;     ...
;   S5_PREFETCH(0);
;   for (int c0 = 0; c0 < SEQ; c0 += T) {
;     const bf16x8 ua = __builtin_bit_cast(bf16x8, pu);
;     if (c0 + T < SEQ) S5_PREFETCH(c0 + T);
.LBB0_1482:
	s_add_i32 s10, s11, 16
	s_cmpk_gt_u32 s10, 0x7ef
	s_cselect_b64 vcc, -1, 0
	v_cndmask_b32_e32 v57, 0, v21, vcc
	s_nor_b64 s[14:15], s[4:5], vcc
	v_cndmask_b32_e32 v56, 0, v20, vcc
	v_cndmask_b32_e32 v55, 0, v19, vcc
	v_cndmask_b32_e32 v54, 0, v18, vcc
	s_and_saveexec_b64 s[8:9], s[14:15]
	s_cbranch_execz .LBB0_1481
	v_add3_u32 v0, v58, s11, 32
	v_cndmask_b32_e64 v54, v71, v0, s[6:7]
	v_ashrrev_i32_e32 v55, 31, v54
	v_lshl_add_u64 v[54:55], v[54:55], 0, s[0:1]
	v_lshlrev_b64 v[54:55], 10, v[54:55]
	v_lshl_add_u64 v[54:55], v[74:75], 0, v[54:55]
	global_load_dwordx4 v[54:57], v[54:55], off nt
	s_branch .LBB0_1481

; DI u32x4 pack8(const float* f) { u32x4 w; w.x = pack2(f[0], f[1]); w.y = pack2(f[2], f[3]); w.z = pack2(f[4], f[5]); w.w = pack2(f[6], f[7]); return w; }
; #define S5_PREFETCH(c0_) do { const int st_ = (c0_) + fr, t_ = dir ? (SEQ - 1 - st_) : st_; \
;     pu = (fq < 2) ? ld8(U + ((size_t)b * SEQ + t_) * 512 + g * 16 + fq * 8) : (u32x4){0u, 0u, 0u, 0u}; } while (0)
; DI void s5_item(const Ctx& c, int item, char* smem) {
;     ...
;   bf16x8 cf[4];
; #pragma unroll
;   for (int ks = 0; ks < 4; ++ks) {
;     float cv[8];
; #pragma unroll
;     for (int jj = 0; jj < 8; ++jj) { const int k = ks * 32 + fq * 8 + jj; const size_t base = ((size_t)(dir * 32 + g) * 16 + fr) * 64; cv[jj] = k < 64 ? p.s5_C_re[base + k] : -p.s5_C_im[base + k - 64]; }
;     cf[ks] = __builtin_bit_cast(bf16x8, pack8(cv));
;   }
;   float xr = 0.f, xi = 0.f;
;   u32x4 pu;
;     ...
;   S5_PREFETCH(0);
.LBB0_1593:
	s_or_b64 exec, exec, s[0:1]
	v_lshlrev_b64 v[14:15], 12, v[0:1]
	v_lshl_or_b32 v14, v56, 8, v14
	v_lshl_add_u64 v[8:9], s[26:27], 0, v[14:15]
	v_readlane_b32 s16, v253, 32
	v_readlane_b32 s17, v253, 33
	v_mov_b32_e32 v1, 0
	v_lshlrev_b32_e32 v0, 2, v13
	v_lshl_add_u64 v[14:15], s[16:17], 0, v[14:15]
	v_lshl_add_u64 v[22:23], v[8:9], 0, v[0:1]
	v_lshl_add_u64 v[14:15], v[14:15], 0, v[0:1]
	global_load_dwordx4 v[38:41], v[22:23], off offset:16 nt
	global_load_dwordx4 v[8:11], v[22:23], off nt
	global_load_dwordx4 v[18:21], v[22:23], off offset:144 nt
	global_load_dwordx4 v[34:37], v[22:23], off offset:128 nt
	s_nop 0
	global_load_dwordx4 v[22:25], v[14:15], off offset:16 nt
	global_load_dwordx4 v[42:45], v[14:15], off nt
	global_load_dwordx4 v[26:29], v[14:15], off offset:144 nt
	global_load_dwordx4 v[30:33], v[14:15], off offset:128 nt
	s_bfe_u32 s14, s96, 0x40003
	s_add_u32 s10, s92, 0x7800000
	s_addc_u32 s11, s93, 0
	s_cmpk_lt_u32 s13, 0x80
	s_cselect_b64 s[2:3], -1, 0
	v_cmp_lt_u32_e64 s[4:5], 31, v117
	v_cmp_gt_u32_e32 vcc, 32, v117
	v_lshlrev_b32_e32 v104, 4, v12
	v_lshlrev_b32_e32 v86, 1, v13
	v_readlane_b32 s18, v253, 34
	v_readlane_b32 s19, v253, 35
	v_readlane_b32 s20, v253, 36
	v_readlane_b32 s21, v253, 37
	v_readlane_b32 s22, v253, 38
	v_readlane_b32 s23, v253, 39
	v_readlane_b32 s24, v253, 40
	v_readlane_b32 s25, v253, 41
	v_readlane_b32 s26, v253, 42
	v_readlane_b32 s27, v253, 43
	v_readlane_b32 s28, v253, 44
	v_readlane_b32 s29, v253, 45
	v_readlane_b32 s30, v253, 46
	v_readlane_b32 s31, v253, 47
	s_and_saveexec_b64 s[0:1], vcc
	s_xor_b64 s[0:1], exec, s[0:1]
	s_cbranch_execz .LBB0_1595
	v_lshlrev_b32_e32 v0, 9, v56
	v_xor_b32_e32 v12, 0xffe00, v0
	v_cndmask_b32_e64 v0, v12, v0, s[2:3]
	v_lshlrev_b32_e32 v0, 1, v0
	v_lshl_or_b32 v0, s14, 21, v0
	v_lshl_add_u64 v[12:13], s[10:11], 0, v[0:1]
	v_ashrrev_i32_e32 v105, 31, v104
	v_lshl_add_u64 v[12:13], v[104:105], 1, v[12:13]
	v_mov_b32_e32 v87, v1
	v_lshl_add_u64 v[0:1], v[12:13], 0, v[86:87]
	global_load_dwordx4 v[12:15], v[0:1], off nt

; #define S5_PREFETCH(c0_) do { const int st_ = (c0_) + fr, t_ = dir ? (SEQ - 1 - st_) : st_; \
;     pu = (fq < 2) ? ld8(U + ((size_t)b * SEQ + t_) * 512 + g * 16 + fq * 8) : (u32x4){0u, 0u, 0u, 0u}; } while (0)
; DI void s5_item(const Ctx& c, int item, char* smem) {
;     ...
;   S5_PREFETCH(0);
;   for (int c0 = 0; c0 < SEQ; c0 += T) {
;     const bf16x8 ua = __builtin_bit_cast(bf16x8, pu);
;     if (c0 + T < SEQ) S5_PREFETCH(c0 + T);
.LBB0_1599:
	s_add_i32 s8, s9, 16
	s_cmpk_gt_u32 s8, 0x7ef
	s_cselect_b64 vcc, -1, 0
	v_cndmask_b32_e32 v55, 0, v15, vcc
	s_nor_b64 s[10:11], s[4:5], vcc
	v_cndmask_b32_e32 v54, 0, v14, vcc
	v_cndmask_b32_e32 v53, 0, v13, vcc
	v_cndmask_b32_e32 v52, 0, v12, vcc
	s_and_saveexec_b64 s[6:7], s[10:11]
	s_cbranch_execz .LBB0_1598
	v_add3_u32 v52, v56, s9, 32
	v_cndmask_b32_e64 v52, v69, v52, s[2:3]
	v_ashrrev_i32_e32 v53, 31, v52
	v_lshl_add_u64 v[52:53], v[52:53], 0, s[0:1]
	v_lshlrev_b64 v[52:53], 10, v[52:53]
	v_lshl_add_u64 v[52:53], v[60:61], 0, v[52:53]
	global_load_dwordx4 v[52:55], v[52:53], off nt
	s_branch .LBB0_1598

; DI void mlstm_item(const Ctx& c, int item, char* smem) {
;     ...
;   const bf16_t* raw = (const bf16_t*)(p.ws + OFF_MLRAW);
;   bf16_t* H = (bf16_t*)(p.ws + OFF_HFB) + (size_t)dir * NTOK * 1024;
;   const float ib = p.ml_i_b[dir * 8 + head], fb = p.ml_f_b[dir * 8 + head];
;   const int cvi = tid & 15, tg = tid >> 4, ch = head * 128 + cvi * 8;
;   float mprev = 0.f;
;   u32x4 px[6]; bf16_t pgi = 0, pgf = 0;
;     ...
;   ML_PREFETCH(0);
.LBB0_1615:
	s_or_b64 exec, exec, s[0:1]
	s_ashr_i32 s0, s89, 8
	s_and_b32 s62, s33, 7
	s_lshl_b32 s76, s0, 3
	s_or_b32 s58, s76, s62
	s_ashr_i32 s59, s58, 31
	v_readlane_b32 s64, v253, 48
	s_lshl_b64 s[58:59], s[58:59], 2
	v_readlane_b32 s66, v253, 50
	v_readlane_b32 s67, v253, 51
	s_add_u32 s60, s66, s58
	v_readlane_b32 s68, v253, 52
	s_addc_u32 s61, s67, s59
	v_readlane_b32 s69, v253, 53
	s_add_u32 s58, s68, s58
	s_addc_u32 s59, s69, s59
	global_load_dword v217, v0, s[60:61]
	global_load_dword v218, v0, s[58:59]
	s_lshl_b32 s33, s62, 7
	v_or_b32_e32 v1, s33, v117
	s_cmpk_lt_u32 s89, 0x100
	s_cselect_b64 s[58:59], -1, 0
	v_lshlrev_b32_e32 v2, 1, v1
	v_mov_b32_e32 v3, v0
	s_cmpk_gt_u32 s89, 0xff
	s_waitcnt vmcnt(18)
	v_cndmask_b32_e64 v34, v187, v186, s[58:59]
	v_lshl_add_u64 v[128:129], s[90:91], 0, v[2:3]
	v_mov_b32_e32 v2, v0
	v_readlane_b32 s70, v253, 54
	s_cselect_b64 s[68:69], -1, 0
	v_add_u32_e32 v16, -1, v34
	s_lshl_b32 s1, s89, 7
	v_mov_b32_e32 v1, v0
	v_mov_b64_e32 v[14:15], v[2:3]
	s_and_b32 s70, s1, 0x7800
	v_cmp_gt_u32_e32 vcc, s83, v16
	v_mov_b64_e32 v[12:13], v[0:1]
	v_readlane_b32 s65, v253, 49
	v_readlane_b32 s71, v253, 55
	s_and_saveexec_b64 s[60:61], vcc
	s_cbranch_execz .LBB0_1617
	v_or_b32_e32 v12, s70, v16
	v_mul_lo_u32 v12, v12, s85
	v_mov_b32_e32 v13, v0
	v_lshl_add_u64 v[12:13], v[12:13], 1, v[128:129]
	global_load_dwordx4 v[12:15], v[12:13], off nt
.LBB0_1617:
	s_or_b64 exec, exec, s[60:61]
	v_or_b32_e32 v16, s70, v34
	v_mul_lo_u32 v32, v16, s85
	v_mov_b64_e32 v[18:19], v[2:3]
	v_cmp_gt_u32_e64 s[60:61], s83, v34
	v_mov_b64_e32 v[16:17], v[0:1]
	s_and_saveexec_b64 s[78:79], s[60:61]
	s_cbranch_execz .LBB0_1619
	v_mov_b32_e32 v33, v0
	v_lshl_add_u64 v[2:3], v[32:33], 1, v[128:129]
	global_load_dwordx4 v[16:19], v[2:3], off nt

.LBB0_1625:
	s_or_b64 exec, exec, s[78:79]
	v_add_u32_e32 v36, 4, v34
	v_mov_b64_e32 v[34:35], v[2:3]
	v_cmp_gt_u32_e32 vcc, s83, v36
	v_mov_b64_e32 v[32:33], v[0:1]
	s_and_saveexec_b64 s[60:61], vcc
	s_cbranch_execz .LBB0_1627
	v_or_b32_e32 v1, s70, v36
	v_mul_lo_u32 v2, v1, s85
	v_mov_b32_e32 v3, v0
	v_lshl_add_u64 v[2:3], v[2:3], 1, v[128:129]
	global_load_dwordx4 v[32:35], v[2:3], off nt

; DI void mlstm_item(const Ctx& c, int item, char* smem) {
;     ...
;     if (c + 1 < SEQ / 64) ML_PREFETCH(c + 1);
.LBB0_1650:
	v_mov_b32_e32 v2, v0
	v_mov_b32_e32 v3, v0
	v_add_u32_e32 v16, -1, v32
	v_mov_b32_e32 v1, v0
	v_mov_b64_e32 v[14:15], v[2:3]
	v_cmp_gt_u32_e32 vcc, s83, v16
	v_mov_b64_e32 v[12:13], v[0:1]
	s_and_saveexec_b64 s[0:1], vcc
	s_cbranch_execz .LBB0_1652
	v_or_b32_e32 v12, s70, v16
	v_mul_lo_u32 v12, v12, s85
	v_mov_b32_e32 v13, v0
	v_lshl_add_u64 v[12:13], v[12:13], 1, v[128:129]
	global_load_dwordx4 v[12:15], v[12:13], off nt
.LBB0_1652:
	s_or_b64 exec, exec, s[0:1]
	v_mov_b64_e32 v[18:19], v[2:3]
	v_cmp_gt_u32_e32 vcc, s83, v32
	v_mov_b64_e32 v[16:17], v[0:1]
	s_and_saveexec_b64 s[0:1], vcc
	s_cbranch_execz .LBB0_1654
	v_or_b32_e32 v1, s70, v32
	v_mul_lo_u32 v2, v1, s85
	v_mov_b32_e32 v3, v0
	v_lshl_add_u64 v[2:3], v[2:3], 1, v[128:129]
	global_load_dwordx4 v[16:19], v[2:3], off nt
.LBB0_1654:
	s_or_b64 exec, exec, s[0:1]
	v_mov_b32_e32 v2, v0
	v_mov_b32_e32 v3, v0
	v_add_u32_e32 v24, 1, v32
	v_mov_b32_e32 v1, v0
	v_mov_b64_e32 v[22:23], v[2:3]
	v_cmp_gt_u32_e32 vcc, s83, v24
	v_mov_b64_e32 v[20:21], v[0:1]
	s_and_saveexec_b64 s[0:1], vcc
	s_cbranch_execz .LBB0_1656
	v_or_b32_e32 v20, s70, v24
	v_mul_lo_u32 v20, v20, s85
	v_mov_b32_e32 v21, v0
	v_lshl_add_u64 v[20:21], v[20:21], 1, v[128:129]
	global_load_dwordx4 v[20:23], v[20:21], off nt
.LBB0_1656:
	s_or_b64 exec, exec, s[0:1]
	v_add_u32_e32 v28, 2, v32
	v_mov_b64_e32 v[26:27], v[2:3]
	v_cmp_gt_u32_e32 vcc, s83, v28
	v_mov_b64_e32 v[24:25], v[0:1]
	s_and_saveexec_b64 s[0:1], vcc
	s_cbranch_execz .LBB0_1658
	v_or_b32_e32 v1, s70, v28
	v_mul_lo_u32 v2, v1, s85
	v_mov_b32_e32 v3, v0
	v_lshl_add_u64 v[2:3], v[2:3], 1, v[128:129]
	global_load_dwordx4 v[24:27], v[2:3], off nt
.LBB0_1658:
	s_or_b64 exec, exec, s[0:1]
	v_mov_b32_e32 v2, v0
	v_mov_b32_e32 v3, v0
	v_add_u32_e32 v33, 3, v32
	v_mov_b32_e32 v1, v0
	v_mov_b64_e32 v[30:31], v[2:3]
	v_cmp_gt_u32_e32 vcc, s83, v33
	v_mov_b64_e32 v[28:29], v[0:1]
	s_and_saveexec_b64 s[0:1], vcc
	s_cbranch_execz .LBB0_1660
	v_or_b32_e32 v28, s70, v33
	v_mul_lo_u32 v28, v28, s85
	v_mov_b32_e32 v29, v0
	v_lshl_add_u64 v[28:29], v[28:29], 1, v[128:129]
	global_load_dwordx4 v[28:31], v[28:29], off nt
.LBB0_1660:
	s_or_b64 exec, exec, s[0:1]
	v_add_u32_e32 v76, 4, v32
	v_mov_b64_e32 v[34:35], v[2:3]
	v_cmp_gt_u32_e32 vcc, s83, v76
	v_mov_b64_e32 v[32:33], v[0:1]
	s_and_saveexec_b64 s[0:1], vcc
	s_cbranch_execz .LBB0_1662
	v_or_b32_e32 v1, s70, v76
	v_mul_lo_u32 v2, v1, s85
	v_mov_b32_e32 v3, v0
	v_lshl_add_u64 v[2:3], v[2:3], 1, v[128:129]
	global_load_dwordx4 v[32:35], v[2:3], off nt
